# v15 + NSA in-projection and xattn q-projection epilogues: the eight per-row rstd loads issued up front into dead registers, one wait, instead of load-wait per row group
# speedup vs baseline: 1.0040x; 1.0000x over previous
.LBB0_700:
	s_lshl_b32 s4, s44, 8
	s_add_i32 s4, s4, s39
	v_or_b32_e32 v142, s4, v137
	v_ashrrev_i32_e32 v143, 31, v142
	v_lshl_add_u64 v[146:147], v[142:143], 2, s[12:13]
	global_load_dword v148, v[146:147], off
	global_load_dword v236, v[146:147], off offset:64
	global_load_dword v237, v[146:147], off offset:128
	global_load_dword v238, v[146:147], off offset:192
	global_load_dword v239, v[146:147], off offset:512
	global_load_dword v240, v[146:147], off offset:576
	global_load_dword v241, v[146:147], off offset:640
	global_load_dword v242, v[146:147], off offset:704
	s_lshl_b32 s17, s43, 8
	s_cmp_gt_i32 s43, 15
	s_cselect_b64 s[24:25], -1, 0
	s_add_i32 s5, s17, 0xfffff000
	s_ashr_i32 s5, s5, 9
	s_bfe_u32 s19, s43, 0x10001
	s_and_b32 s5, s5, 0x1ffffffe
	s_or_b32 s5, s5, s19
	s_ashr_i32 s4, s4, 11
	v_lshlrev_b32_e32 v144, 7, v142
	s_lshl_b32 s19, s5, 3
	s_and_b32 s4, s4, -4
	v_and_b32_e32 v144, 0xfe780, v144
	s_add_i32 s33, s19, s4
	s_mov_b64 s[4:5], -1
	s_and_b64 vcc, exec, s[24:25]
	v_lshlrev_b32_e32 v144, 1, v144
	s_waitcnt vmcnt(0)
	v_pk_mul_f32 v[152:153], v[126:127], v[148:149] op_sel_hi:[1,0]
	v_pk_mul_f32 v[156:157], v[124:125], v[148:149] op_sel_hi:[1,0]
	v_pk_mul_f32 v[150:151], v[122:123], v[148:149] op_sel_hi:[1,0]
	v_pk_mul_f32 v[154:155], v[120:121], v[148:149] op_sel_hi:[1,0]
	v_lshlrev_b32_e32 v124, 1, v136
	s_cbranch_vccz .LBB0_702
	s_lshr_b32 s4, s17, 7
	s_and_b32 s4, s4, 2
	s_or_b32 s4, s33, s4
	s_ashr_i32 s5, s4, 31
	s_lshl_b64 s[4:5], s[4:5], 21
	s_add_u32 s4, s10, s4
	s_addc_u32 s5, s11, s5
	v_lshl_add_u64 v[126:127], s[4:5], 0, v[144:145]
	v_mov_b32_e32 v125, v145
	v_cvt_pk_bf16_f32 v120, v156, v157
	v_cvt_pk_bf16_f32 v121, v152, v153
	v_cvt_pk_bf16_f32 v122, v154, v155
	v_cvt_pk_bf16_f32 v123, v150, v151
	v_lshl_add_u64 v[160:161], v[126:127], 0, v[124:125]
	s_mov_b64 s[4:5], 0

.LBB0_708:
	global_store_dwordx4 v[148:149], v[112:115], off
	s_nop 1
	v_mov_b32_e32 v112, v236
	s_mov_b64 s[24:25], -1
	v_or_b32_e32 v114, 16, v142
	v_lshlrev_b32_e32 v113, 7, v114
	v_and_b32_e32 v113, 0xfef80, v113
	s_and_b64 vcc, exec, s[4:5]
	v_lshlrev_b32_e32 v144, 1, v113
	v_pk_mul_f32 v[118:119], v[110:111], v[112:113] op_sel_hi:[1,0]
	v_pk_mul_f32 v[122:123], v[108:109], v[112:113] op_sel_hi:[1,0]
	v_pk_mul_f32 v[110:111], v[106:107], v[112:113] op_sel_hi:[1,0]
	v_pk_mul_f32 v[120:121], v[104:105], v[112:113] op_sel_hi:[1,0]
	s_cbranch_vccnz .LBB0_710
	s_lshr_b32 s24, s17, 7
	s_and_b32 s24, s24, 2
	s_or_b32 s24, s33, s24
	s_ashr_i32 s25, s24, 31
	s_lshl_b64 s[24:25], s[24:25], 21
	s_add_u32 s24, s10, s24
	s_addc_u32 s25, s11, s25
	v_lshl_add_u64 v[108:109], s[24:25], 0, v[144:145]
	v_mov_b32_e32 v125, v145
	v_lshl_add_u64 v[148:149], v[108:109], 0, v[124:125]
	s_mov_b64 s[24:25], 0
	v_cvt_pk_bf16_f32 v104, v122, v123
	v_cvt_pk_bf16_f32 v105, v118, v119
	v_cvt_pk_bf16_f32 v106, v120, v121
	v_cvt_pk_bf16_f32 v107, v110, v111

.LBB0_716:
	global_store_dwordx4 v[110:111], v[96:99], off
	s_nop 1
	v_mov_b32_e32 v96, v237
	s_mov_b64 s[24:25], -1
	v_or_b32_e32 v98, 32, v142
	v_lshlrev_b32_e32 v97, 7, v98
	v_and_b32_e32 v97, 0xff780, v97
	s_and_b64 vcc, exec, s[4:5]
	v_lshlrev_b32_e32 v144, 1, v97
	v_pk_mul_f32 v[100:101], v[94:95], v[96:97] op_sel_hi:[1,0]
	v_pk_mul_f32 v[104:105], v[92:93], v[96:97] op_sel_hi:[1,0]
	v_pk_mul_f32 v[94:95], v[90:91], v[96:97] op_sel_hi:[1,0]
	v_pk_mul_f32 v[102:103], v[88:89], v[96:97] op_sel_hi:[1,0]
	s_cbranch_vccnz .LBB0_718
	s_lshr_b32 s24, s17, 7
	s_and_b32 s24, s24, 2
	s_or_b32 s24, s33, s24
	s_ashr_i32 s25, s24, 31
	s_lshl_b64 s[24:25], s[24:25], 21
	s_add_u32 s24, s10, s24
	s_addc_u32 s25, s11, s25
	v_lshl_add_u64 v[92:93], s[24:25], 0, v[144:145]
	v_mov_b32_e32 v125, v145
	v_lshl_add_u64 v[106:107], v[92:93], 0, v[124:125]
	s_mov_b64 s[24:25], 0
	v_cvt_pk_bf16_f32 v88, v104, v105
	v_cvt_pk_bf16_f32 v89, v100, v101
	v_cvt_pk_bf16_f32 v90, v102, v103
	v_cvt_pk_bf16_f32 v91, v94, v95

.LBB0_724:
	global_store_dwordx4 v[94:95], v[80:83], off
	s_nop 1
	v_mov_b32_e32 v80, v238
	s_mov_b64 s[24:25], -1
	v_or_b32_e32 v82, 48, v142
	v_lshlrev_b32_e32 v81, 7, v82
	v_and_b32_e32 v81, 0xfff80, v81
	s_and_b64 vcc, exec, s[4:5]
	v_lshlrev_b32_e32 v144, 1, v81
	v_pk_mul_f32 v[84:85], v[78:79], v[80:81] op_sel_hi:[1,0]
	v_pk_mul_f32 v[88:89], v[76:77], v[80:81] op_sel_hi:[1,0]
	v_pk_mul_f32 v[78:79], v[74:75], v[80:81] op_sel_hi:[1,0]
	v_pk_mul_f32 v[86:87], v[72:73], v[80:81] op_sel_hi:[1,0]
	s_cbranch_vccnz .LBB0_726
	s_lshr_b32 s24, s17, 7
	s_and_b32 s24, s24, 2
	s_or_b32 s24, s33, s24
	s_ashr_i32 s25, s24, 31
	s_lshl_b64 s[24:25], s[24:25], 21
	s_add_u32 s24, s10, s24
	s_addc_u32 s25, s11, s25
	v_lshl_add_u64 v[76:77], s[24:25], 0, v[144:145]
	v_mov_b32_e32 v125, v145
	v_lshl_add_u64 v[90:91], v[76:77], 0, v[124:125]
	s_mov_b64 s[24:25], 0
	v_cvt_pk_bf16_f32 v72, v88, v89
	v_cvt_pk_bf16_f32 v73, v84, v85
	v_cvt_pk_bf16_f32 v74, v86, v87
	v_cvt_pk_bf16_f32 v75, v78, v79

.LBB0_732:
	global_store_dwordx4 v[78:79], v[64:67], off
	s_mov_b64 s[24:25], -1
	s_and_b64 vcc, exec, s[4:5]
	v_add_u32_e32 v66, 0x80, v142
	v_ashrrev_i32_e32 v64, 11, v66
	v_and_b32_e32 v64, -4, v64
	v_add_u32_e32 v74, s19, v64
	v_mov_b32_e32 v64, v239
	v_lshlrev_b32_e32 v65, 7, v66
	v_and_b32_e32 v65, 0xfe780, v65
	v_lshlrev_b32_e32 v144, 1, v65
	v_pk_mul_f32 v[62:63], v[62:63], v[64:65] op_sel_hi:[1,0]
	v_pk_mul_f32 v[70:71], v[60:61], v[64:65] op_sel_hi:[1,0]
	v_pk_mul_f32 v[60:61], v[58:59], v[64:65] op_sel_hi:[1,0]
	v_pk_mul_f32 v[68:69], v[56:57], v[64:65] op_sel_hi:[1,0]
	s_cbranch_vccnz .LBB0_734
	s_lshr_b32 s19, s17, 7
	v_and_or_b32 v72, s19, 2, v74
	v_ashrrev_i32_e32 v73, 31, v72
	v_lshlrev_b64 v[72:73], 21, v[72:73]
	v_lshl_add_u64 v[72:73], s[10:11], 0, v[72:73]
	v_lshl_add_u64 v[72:73], v[72:73], 0, v[144:145]
	v_mov_b32_e32 v125, v145
	v_lshl_add_u64 v[72:73], v[72:73], 0, v[124:125]
	s_mov_b64 s[24:25], 0
	v_cvt_pk_bf16_f32 v56, v70, v71
	v_cvt_pk_bf16_f32 v57, v62, v63
	v_cvt_pk_bf16_f32 v58, v68, v69
	v_cvt_pk_bf16_f32 v59, v60, v61

.LBB0_740:
	global_store_dwordx4 v[62:63], v[48:51], off
	s_nop 1
	v_mov_b32_e32 v48, v240
	s_mov_b64 s[24:25], -1
	v_add_u32_e32 v50, 0x90, v142
	v_lshlrev_b32_e32 v49, 7, v50
	v_and_b32_e32 v49, 0xfef80, v49
	s_and_b64 vcc, exec, s[4:5]
	v_lshlrev_b32_e32 v144, 1, v49
	v_pk_mul_f32 v[54:55], v[46:47], v[48:49] op_sel_hi:[1,0]
	v_pk_mul_f32 v[58:59], v[44:45], v[48:49] op_sel_hi:[1,0]
	v_pk_mul_f32 v[46:47], v[42:43], v[48:49] op_sel_hi:[1,0]
	v_pk_mul_f32 v[56:57], v[40:41], v[48:49] op_sel_hi:[1,0]
	s_cbranch_vccnz .LBB0_742
	s_lshr_b32 s19, s17, 7
	v_and_or_b32 v44, s19, 2, v74
	v_ashrrev_i32_e32 v45, 31, v44
	v_lshlrev_b64 v[44:45], 21, v[44:45]
	v_lshl_add_u64 v[44:45], s[10:11], 0, v[44:45]
	v_lshl_add_u64 v[44:45], v[44:45], 0, v[144:145]
	v_mov_b32_e32 v125, v145
	v_lshl_add_u64 v[60:61], v[44:45], 0, v[124:125]
	s_mov_b64 s[24:25], 0
	v_cvt_pk_bf16_f32 v40, v58, v59
	v_cvt_pk_bf16_f32 v41, v54, v55
	v_cvt_pk_bf16_f32 v42, v56, v57
	v_cvt_pk_bf16_f32 v43, v46, v47

.LBB0_748:
	global_store_dwordx4 v[46:47], v[32:35], off
	s_nop 1
	v_mov_b32_e32 v32, v241
	s_mov_b64 s[24:25], -1
	v_add_u32_e32 v34, 0xa0, v142
	v_lshlrev_b32_e32 v33, 7, v34
	v_and_b32_e32 v33, 0xff780, v33
	s_and_b64 vcc, exec, s[4:5]
	v_lshlrev_b32_e32 v144, 1, v33
	v_pk_mul_f32 v[36:37], v[30:31], v[32:33] op_sel_hi:[1,0]
	v_pk_mul_f32 v[40:41], v[28:29], v[32:33] op_sel_hi:[1,0]
	v_pk_mul_f32 v[30:31], v[26:27], v[32:33] op_sel_hi:[1,0]
	v_pk_mul_f32 v[38:39], v[24:25], v[32:33] op_sel_hi:[1,0]
	s_cbranch_vccnz .LBB0_750
	s_lshr_b32 s19, s17, 7
	v_and_or_b32 v28, s19, 2, v74
	v_ashrrev_i32_e32 v29, 31, v28
	v_lshlrev_b64 v[28:29], 21, v[28:29]
	v_lshl_add_u64 v[28:29], s[10:11], 0, v[28:29]
	v_lshl_add_u64 v[28:29], v[28:29], 0, v[144:145]
	v_mov_b32_e32 v125, v145
	v_lshl_add_u64 v[42:43], v[28:29], 0, v[124:125]
	s_mov_b64 s[24:25], 0
	v_cvt_pk_bf16_f32 v24, v40, v41
	v_cvt_pk_bf16_f32 v25, v36, v37
	v_cvt_pk_bf16_f32 v26, v38, v39
	v_cvt_pk_bf16_f32 v27, v30, v31

.LBB0_756:
	global_store_dwordx4 v[30:31], v[16:19], off
	s_nop 1
	v_mov_b32_e32 v16, v242
	s_mov_b64 s[24:25], -1
	v_add_u32_e32 v18, 0xb0, v142
	v_lshlrev_b32_e32 v17, 7, v18
	v_and_b32_e32 v17, 0xfff80, v17
	s_and_b64 vcc, exec, s[4:5]
	v_lshlrev_b32_e32 v144, 1, v17
	v_pk_mul_f32 v[20:21], v[14:15], v[16:17] op_sel_hi:[1,0]
	v_pk_mul_f32 v[24:25], v[12:13], v[16:17] op_sel_hi:[1,0]
	v_pk_mul_f32 v[14:15], v[10:11], v[16:17] op_sel_hi:[1,0]
	v_pk_mul_f32 v[22:23], v[8:9], v[16:17] op_sel_hi:[1,0]
	s_cbranch_vccnz .LBB0_758
	s_lshr_b32 s17, s17, 7
	v_and_or_b32 v12, s17, 2, v74
	v_ashrrev_i32_e32 v13, 31, v12
	v_lshlrev_b64 v[12:13], 21, v[12:13]
	v_lshl_add_u64 v[12:13], s[10:11], 0, v[12:13]
	v_lshl_add_u64 v[12:13], v[12:13], 0, v[144:145]
	v_mov_b32_e32 v125, v145
	v_lshl_add_u64 v[26:27], v[12:13], 0, v[124:125]
	s_mov_b64 s[24:25], 0
	v_cvt_pk_bf16_f32 v8, v24, v25
	v_cvt_pk_bf16_f32 v9, v20, v21
	v_cvt_pk_bf16_f32 v10, v22, v23
	v_cvt_pk_bf16_f32 v11, v14, v15

.LBB0_1761:
	v_lshl_add_u32 v148, s45, 8, v142
	v_ashrrev_i32_e32 v149, 31, v148
	v_lshl_add_u64 v[140:141], v[148:149], 2, s[12:13]
	global_load_dword v150, v[140:141], off
	global_load_dword v232, v[140:141], off offset:64
	global_load_dword v233, v[140:141], off offset:128
	global_load_dword v234, v[140:141], off offset:192
	global_load_dword v235, v[140:141], off offset:512
	global_load_dword v236, v[140:141], off offset:576
	global_load_dword v237, v[140:141], off offset:640
	global_load_dword v238, v[140:141], off offset:704
	v_lshl_or_b32 v138, s44, 8, v146
	v_ashrrev_i32_e32 v139, 31, v138
	v_lshl_add_u64 v[152:153], v[138:139], 1, s[8:9]
	v_lshlrev_b64 v[138:139], 10, v[148:149]
	v_lshl_add_u64 v[138:139], v[152:153], 0, v[138:139]
	s_mov_b64 s[10:11], 0x20000
	s_waitcnt vmcnt(0)
	v_pk_mul_f32 v[126:127], v[126:127], v[150:151] op_sel_hi:[1,0]
	v_pk_mul_f32 v[124:125], v[124:125], v[150:151] op_sel_hi:[1,0]
	v_pk_mul_f32 v[122:123], v[122:123], v[150:151] op_sel_hi:[1,0]
	v_pk_mul_f32 v[120:121], v[120:121], v[150:151] op_sel_hi:[1,0]
	v_pk_mul_f32 v[118:119], v[118:119], v[150:151] op_sel_hi:[1,0]
	v_pk_mul_f32 v[116:117], v[116:117], v[150:151] op_sel_hi:[1,0]
	v_pk_mul_f32 v[154:155], v[114:115], v[150:151] op_sel_hi:[1,0]
	v_pk_mul_f32 v[150:151], v[112:113], v[150:151] op_sel_hi:[1,0]
	v_cvt_pk_bf16_f32 v112, v124, v125
	v_cvt_pk_bf16_f32 v113, v126, v127
	v_cvt_pk_bf16_f32 v114, v120, v121
	v_cvt_pk_bf16_f32 v115, v122, v123
	global_store_dwordx4 v[138:139], v[112:115], off
	s_nop 1
	v_cvt_pk_bf16_f32 v112, v116, v117
	v_cvt_pk_bf16_f32 v113, v118, v119
	v_cvt_pk_bf16_f32 v114, v150, v151
	v_cvt_pk_bf16_f32 v115, v154, v155
	global_store_dwordx4 v[138:139], v[112:115], off offset:256
	s_nop 1
	v_mov_b32_e32 v112, v232
	v_pk_mul_f32 v[110:111], v[110:111], v[112:113] op_sel_hi:[1,0]
	v_or_b32_e32 v114, 16, v148
	v_ashrrev_i32_e32 v115, 31, v114
	v_lshlrev_b64 v[114:115], 10, v[114:115]
	v_lshl_add_u64 v[114:115], v[152:153], 0, v[114:115]
	v_pk_mul_f32 v[108:109], v[108:109], v[112:113] op_sel_hi:[1,0]
	v_pk_mul_f32 v[106:107], v[106:107], v[112:113] op_sel_hi:[1,0]
	v_pk_mul_f32 v[104:105], v[104:105], v[112:113] op_sel_hi:[1,0]
	v_pk_mul_f32 v[102:103], v[102:103], v[112:113] op_sel_hi:[1,0]
	v_pk_mul_f32 v[100:101], v[100:101], v[112:113] op_sel_hi:[1,0]
	v_pk_mul_f32 v[116:117], v[98:99], v[112:113] op_sel_hi:[1,0]
	v_pk_mul_f32 v[112:113], v[96:97], v[112:113] op_sel_hi:[1,0]
	v_cvt_pk_bf16_f32 v96, v108, v109
	v_cvt_pk_bf16_f32 v97, v110, v111
	v_cvt_pk_bf16_f32 v98, v104, v105
	v_cvt_pk_bf16_f32 v99, v106, v107
	global_store_dwordx4 v[114:115], v[96:99], off
	s_nop 1
	v_cvt_pk_bf16_f32 v96, v100, v101
	v_cvt_pk_bf16_f32 v97, v102, v103
	v_cvt_pk_bf16_f32 v98, v112, v113
	v_cvt_pk_bf16_f32 v99, v116, v117
	global_store_dwordx4 v[114:115], v[96:99], off offset:256
	s_nop 1
	v_mov_b32_e32 v96, v233
	v_pk_mul_f32 v[94:95], v[94:95], v[96:97] op_sel_hi:[1,0]
	v_or_b32_e32 v98, 32, v148
	v_ashrrev_i32_e32 v99, 31, v98
	v_lshlrev_b64 v[98:99], 10, v[98:99]
	v_lshl_add_u64 v[98:99], v[152:153], 0, v[98:99]
	v_pk_mul_f32 v[92:93], v[92:93], v[96:97] op_sel_hi:[1,0]
	v_pk_mul_f32 v[90:91], v[90:91], v[96:97] op_sel_hi:[1,0]
	v_pk_mul_f32 v[88:89], v[88:89], v[96:97] op_sel_hi:[1,0]
	v_pk_mul_f32 v[86:87], v[86:87], v[96:97] op_sel_hi:[1,0]
	v_pk_mul_f32 v[84:85], v[84:85], v[96:97] op_sel_hi:[1,0]
	v_pk_mul_f32 v[100:101], v[82:83], v[96:97] op_sel_hi:[1,0]
	v_pk_mul_f32 v[96:97], v[80:81], v[96:97] op_sel_hi:[1,0]
	v_cvt_pk_bf16_f32 v80, v92, v93
	v_cvt_pk_bf16_f32 v81, v94, v95
	v_cvt_pk_bf16_f32 v82, v88, v89
	v_cvt_pk_bf16_f32 v83, v90, v91
	global_store_dwordx4 v[98:99], v[80:83], off
	s_nop 1
	v_cvt_pk_bf16_f32 v80, v84, v85
	v_cvt_pk_bf16_f32 v81, v86, v87
	v_cvt_pk_bf16_f32 v82, v96, v97
	v_cvt_pk_bf16_f32 v83, v100, v101
	global_store_dwordx4 v[98:99], v[80:83], off offset:256
	s_nop 1
	v_mov_b32_e32 v80, v234
	v_pk_mul_f32 v[78:79], v[78:79], v[80:81] op_sel_hi:[1,0]
	v_or_b32_e32 v82, 48, v148
	v_ashrrev_i32_e32 v83, 31, v82
	v_lshlrev_b64 v[82:83], 10, v[82:83]
	v_lshl_add_u64 v[82:83], v[152:153], 0, v[82:83]
	v_pk_mul_f32 v[76:77], v[76:77], v[80:81] op_sel_hi:[1,0]
	v_pk_mul_f32 v[74:75], v[74:75], v[80:81] op_sel_hi:[1,0]
	v_pk_mul_f32 v[72:73], v[72:73], v[80:81] op_sel_hi:[1,0]
	v_pk_mul_f32 v[70:71], v[70:71], v[80:81] op_sel_hi:[1,0]
	v_pk_mul_f32 v[68:69], v[68:69], v[80:81] op_sel_hi:[1,0]
	v_pk_mul_f32 v[84:85], v[66:67], v[80:81] op_sel_hi:[1,0]
	v_pk_mul_f32 v[80:81], v[64:65], v[80:81] op_sel_hi:[1,0]
	v_cvt_pk_bf16_f32 v64, v76, v77
	v_cvt_pk_bf16_f32 v65, v78, v79
	v_cvt_pk_bf16_f32 v66, v72, v73
	v_cvt_pk_bf16_f32 v67, v74, v75
	global_store_dwordx4 v[82:83], v[64:67], off
	s_nop 1
	v_cvt_pk_bf16_f32 v64, v68, v69
	v_cvt_pk_bf16_f32 v65, v70, v71
	v_cvt_pk_bf16_f32 v66, v80, v81
	v_cvt_pk_bf16_f32 v67, v84, v85
	global_store_dwordx4 v[82:83], v[64:67], off offset:256
	s_nop 1
	v_mov_b32_e32 v64, v235
	v_pk_mul_f32 v[62:63], v[62:63], v[64:65] op_sel_hi:[1,0]
	v_lshl_add_u64 v[66:67], v[138:139], 0, s[10:11]
	s_mov_b32 s10, 0x20000
	v_add_co_u32_e32 v68, vcc, s10, v138
	v_pk_mul_f32 v[60:61], v[60:61], v[64:65] op_sel_hi:[1,0]
	s_nop 0
	v_addc_co_u32_e32 v69, vcc, 0, v139, vcc
	v_pk_mul_f32 v[58:59], v[58:59], v[64:65] op_sel_hi:[1,0]
	v_pk_mul_f32 v[56:57], v[56:57], v[64:65] op_sel_hi:[1,0]
	v_pk_mul_f32 v[54:55], v[54:55], v[64:65] op_sel_hi:[1,0]
	v_pk_mul_f32 v[52:53], v[52:53], v[64:65] op_sel_hi:[1,0]
	v_pk_mul_f32 v[70:71], v[50:51], v[64:65] op_sel_hi:[1,0]
	v_pk_mul_f32 v[64:65], v[48:49], v[64:65] op_sel_hi:[1,0]
	v_cvt_pk_bf16_f32 v48, v60, v61
	v_cvt_pk_bf16_f32 v49, v62, v63
	v_cvt_pk_bf16_f32 v50, v56, v57
	v_cvt_pk_bf16_f32 v51, v58, v59
	global_store_dwordx4 v[68:69], v[48:51], off
	s_mov_b64 s[10:11], 0x24000
	s_nop 0
	v_cvt_pk_bf16_f32 v48, v52, v53
	v_cvt_pk_bf16_f32 v49, v54, v55
	v_cvt_pk_bf16_f32 v50, v64, v65
	v_cvt_pk_bf16_f32 v51, v70, v71
	global_store_dwordx4 v[66:67], v[48:51], off offset:256
	s_nop 1
	v_mov_b32_e32 v48, v236
	v_pk_mul_f32 v[46:47], v[46:47], v[48:49] op_sel_hi:[1,0]
	v_lshl_add_u64 v[50:51], v[138:139], 0, s[10:11]
	s_mov_b32 s10, 0x24000
	v_add_co_u32_e32 v52, vcc, s10, v138
	v_pk_mul_f32 v[44:45], v[44:45], v[48:49] op_sel_hi:[1,0]
	s_nop 0
	v_addc_co_u32_e32 v53, vcc, 0, v139, vcc
	v_pk_mul_f32 v[42:43], v[42:43], v[48:49] op_sel_hi:[1,0]
	v_pk_mul_f32 v[40:41], v[40:41], v[48:49] op_sel_hi:[1,0]
	v_pk_mul_f32 v[38:39], v[38:39], v[48:49] op_sel_hi:[1,0]
	v_pk_mul_f32 v[36:37], v[36:37], v[48:49] op_sel_hi:[1,0]
	v_pk_mul_f32 v[54:55], v[34:35], v[48:49] op_sel_hi:[1,0]
	v_pk_mul_f32 v[48:49], v[32:33], v[48:49] op_sel_hi:[1,0]
	v_cvt_pk_bf16_f32 v32, v44, v45
	v_cvt_pk_bf16_f32 v33, v46, v47
	v_cvt_pk_bf16_f32 v34, v40, v41
	v_cvt_pk_bf16_f32 v35, v42, v43
	global_store_dwordx4 v[52:53], v[32:35], off
	s_mov_b64 s[10:11], 0x28000
	s_nop 0
	v_cvt_pk_bf16_f32 v32, v36, v37
	v_cvt_pk_bf16_f32 v33, v38, v39
	v_cvt_pk_bf16_f32 v34, v48, v49
	v_cvt_pk_bf16_f32 v35, v54, v55
	global_store_dwordx4 v[50:51], v[32:35], off offset:256
	s_nop 1
	v_mov_b32_e32 v32, v237
	v_pk_mul_f32 v[30:31], v[30:31], v[32:33] op_sel_hi:[1,0]
	v_lshl_add_u64 v[34:35], v[138:139], 0, s[10:11]
	s_mov_b32 s10, 0x28000
	v_add_co_u32_e32 v36, vcc, s10, v138
	v_pk_mul_f32 v[28:29], v[28:29], v[32:33] op_sel_hi:[1,0]
	s_nop 0
	v_addc_co_u32_e32 v37, vcc, 0, v139, vcc
	v_pk_mul_f32 v[26:27], v[26:27], v[32:33] op_sel_hi:[1,0]
	v_pk_mul_f32 v[24:25], v[24:25], v[32:33] op_sel_hi:[1,0]
	v_pk_mul_f32 v[22:23], v[22:23], v[32:33] op_sel_hi:[1,0]
	v_pk_mul_f32 v[20:21], v[20:21], v[32:33] op_sel_hi:[1,0]
	v_pk_mul_f32 v[38:39], v[18:19], v[32:33] op_sel_hi:[1,0]
	v_pk_mul_f32 v[32:33], v[16:17], v[32:33] op_sel_hi:[1,0]
	v_cvt_pk_bf16_f32 v16, v28, v29
	v_cvt_pk_bf16_f32 v17, v30, v31
	v_cvt_pk_bf16_f32 v18, v24, v25
	v_cvt_pk_bf16_f32 v19, v26, v27
	global_store_dwordx4 v[36:37], v[16:19], off
	s_andn2_b64 vcc, exec, s[2:3]
	s_mov_b64 s[2:3], 0x2c000
	v_cvt_pk_bf16_f32 v16, v20, v21
	v_cvt_pk_bf16_f32 v17, v22, v23
	v_cvt_pk_bf16_f32 v18, v32, v33
	v_cvt_pk_bf16_f32 v19, v38, v39
	global_store_dwordx4 v[34:35], v[16:19], off offset:256
	s_nop 1
	v_mov_b32_e32 v16, v238
	v_pk_mul_f32 v[14:15], v[14:15], v[16:17] op_sel_hi:[1,0]
	v_lshl_add_u64 v[18:19], v[138:139], 0, s[2:3]
	s_mov_b32 s2, 0x2c000
	v_add_co_u32_e64 v20, s[2:3], s2, v138
	v_pk_mul_f32 v[12:13], v[12:13], v[16:17] op_sel_hi:[1,0]
	s_nop 0
	v_addc_co_u32_e64 v21, s[2:3], 0, v139, s[2:3]
	v_pk_mul_f32 v[10:11], v[10:11], v[16:17] op_sel_hi:[1,0]
	v_pk_mul_f32 v[8:9], v[8:9], v[16:17] op_sel_hi:[1,0]
	v_pk_mul_f32 v[6:7], v[6:7], v[16:17] op_sel_hi:[1,0]
	v_pk_mul_f32 v[4:5], v[4:5], v[16:17] op_sel_hi:[1,0]
	v_pk_mul_f32 v[22:23], v[2:3], v[16:17] op_sel_hi:[1,0]
	v_pk_mul_f32 v[16:17], v[0:1], v[16:17] op_sel_hi:[1,0]
	v_cvt_pk_bf16_f32 v0, v12, v13
	v_cvt_pk_bf16_f32 v1, v14, v15
	v_cvt_pk_bf16_f32 v2, v8, v9
	v_cvt_pk_bf16_f32 v3, v10, v11
	s_mov_b64 s[2:3], -1
	global_store_dwordx4 v[20:21], v[0:3], off
	s_nop 1
	v_cvt_pk_bf16_f32 v0, v4, v5
	v_cvt_pk_bf16_f32 v1, v6, v7
	v_cvt_pk_bf16_f32 v2, v16, v17
	v_cvt_pk_bf16_f32 v3, v22, v23
	global_store_dwordx4 v[18:19], v[0:3], off offset:256
	s_cbranch_vccnz .LBB0_1750
	s_andn2_b64 vcc, exec, s[6:7]
	s_cbranch_vccnz .LBB0_1749
	s_barrier
	s_branch .LBB0_1749
